# adds exec=0 dry-run instruction prefetch on the four P4 weight-conversion variants
# baseline (speedup 1.0000x reference)
; #define LAS __attribute__((address_space(3)))
; __device__ __forceinline__ unsigned pk2(float lo, float hi) { return f2bf(lo) | (f2bf(hi) << 16); }
; __device__ __forceinline__ void p0_transpose_kn(const float* W, int K, int N, bf16_t* WT, int row_off, LAS float* scr, int kb, int nb, int lane) {
;     const int k0 = 64 * kb, n0 = 32 * nb;
;     float wv[32];
; #pragma unroll
;     for (int i = 0; i < 32; ++i) wv[i] = W[(size_t)(k0 + 2 * i + (lane >> 5)) * N + n0 + (lane & 31)];
; #pragma unroll
;     for (int i = 0; i < 32; ++i) scr[(2 * i + (lane >> 5)) * 33 + (lane & 31)] = wv[i];
;     asm volatile("s_waitcnt lgkmcnt(0)" ::: "memory");
;     const int c = lane & 7;
; #pragma unroll
;     for (int j = 0; j < 4; ++j) { const int n = (lane >> 3) + 8 * j; const LAS float* s = scr + (8 * c) * 33 + n;
;         u32x4 o; o.x = pk2(s[0 * 33], s[1 * 33]); o.y = pk2(s[2 * 33], s[3 * 33]); o.z = pk2(s[4 * 33], s[5 * 33]); o.w = pk2(s[6 * 33], s[7 * 33]);
;         *(u32x4*)(WT + (size_t)(row_off + n0 + n) * K + k0 + 8 * c) = o; }
;     asm volatile("s_waitcnt lgkmcnt(0)" ::: "memory");
; }
; __global__ void __launch_bounds__(512, 2) mk_fwd(Args args) {
;     ...
;             for (int it = gw; it < 16 * 128 + 3 * 512; it += NGW) {
;                 int r = it;
;                 if (r < 16 * 128) { const int kb = r / 128, j = r % 128, sg = j >> 5, seg = sg == 0 ? 3 : sg + 6; p0_transpose_kn(w_in, 1024, 10240, Wt_in, 0, scr, kb, seg * 32 + (j & 31), lane); continue; } r -= 16 * 128;
;                 if (r < 512) { p0_transpose_kn(w_sb, 1024, 1024, Wt_sbhg, 0, scr, r / 32, r % 32, lane); continue; } r -= 512;
;                 if (r < 512) { p0_transpose_kn(w_hg, 1024, 1024, Wt_sbhg, 1024, scr, r / 32, r % 32, lane); continue; } r -= 512;
;                 p0_transpose_kn(w_out, 1024, 1024, Wt_out, 0, scr, r / 32, r % 32, lane);
.LBB0_403:
	v_cmp_lt_i32_e32 vcc, s16, v169
	s_and_saveexec_b64 s[8:9], vcc
	s_xor_b64 s[8:9], exec, s[8:9]
	s_cbranch_execz .LBB0_413
	v_cmp_lt_u32_e32 vcc, s17, v169
	v_and_b32_e32 v16, 0x3e0, v26
	s_and_saveexec_b64 s[10:11], vcc
	s_xor_b64 s[10:11], exec, s[10:11]
	s_cbranch_execz .LBB0_410
	v_cmp_lt_u32_e32 vcc, s18, v169
	s_and_saveexec_b64 s[12:13], vcc
	s_xor_b64 s[12:13], exec, s[12:13]
	s_cbranch_execz .LBB0_407
	v_readfirstlane_b32 s98, v200
	s_nop 0
	s_lshr_b32 s98, s98, 6
	s_cmp_eq_u32 s98, 0
	s_cbranch_scc1 .Ldry_cvA_real
	s_mov_b64 exec, 0
	s_cmp_eq_u32 s98, 1
	s_cbranch_scc1 .Ldry_cvA_c1
	s_cmp_eq_u32 s98, 2
	s_cbranch_scc1 .Ldry_cvA_c2
	s_cmp_eq_u32 s98, 3
	s_cbranch_scc1 .Ldry_cvA_c3
	s_cmp_eq_u32 s98, 4
	s_cbranch_scc1 .Ldry_cvA_c4
	s_cmp_eq_u32 s98, 5
	s_cbranch_scc1 .Ldry_cvA_c5
	s_cmp_eq_u32 s98, 6
	s_cbranch_scc1 .Ldry_cvA_c6
	s_branch .Ldry_cvA_c7
.Ldry_cvA_real:
	s_mov_b64 exec, -1
	v_and_b32_e32 v0, 0x7fffffc0, v25
	v_add_u32_e32 v36, 0xffffe800, v0
	v_or_b32_e32 v38, v36, v18
	v_lshlrev_b32_e32 v0, 2, v16
	v_lshl_add_u64 v[40:41], v[2:3], 0, v[0:1]
	v_or_b32_e32 v0, 2, v38
	v_lshlrev_b64 v[44:45], 12, v[0:1]
	v_or_b32_e32 v0, 4, v38
	v_lshlrev_b64 v[46:47], 12, v[0:1]
	v_or_b32_e32 v0, 6, v38
	v_lshlrev_b64 v[48:49], 12, v[0:1]
	v_or_b32_e32 v0, 8, v38
	v_lshlrev_b64 v[50:51], 12, v[0:1]
	v_or_b32_e32 v0, 10, v38
	v_mov_b32_e32 v39, v1
	v_lshlrev_b64 v[52:53], 12, v[0:1]
	v_or_b32_e32 v0, 12, v38
	v_lshlrev_b64 v[42:43], 12, v[38:39]
	v_lshlrev_b64 v[54:55], 12, v[0:1]
	v_or_b32_e32 v0, 14, v38
	v_lshl_add_u64 v[42:43], v[40:41], 0, v[42:43]
	v_lshlrev_b64 v[56:57], 12, v[0:1]
	v_or_b32_e32 v0, 16, v38
	v_lshl_add_u64 v[44:45], v[40:41], 0, v[44:45]
	v_lshl_add_u64 v[46:47], v[40:41], 0, v[46:47]
	v_lshl_add_u64 v[48:49], v[40:41], 0, v[48:49]
	v_lshl_add_u64 v[50:51], v[40:41], 0, v[50:51]
	v_lshl_add_u64 v[52:53], v[40:41], 0, v[52:53]
	v_lshl_add_u64 v[54:55], v[40:41], 0, v[54:55]
	v_lshl_add_u64 v[56:57], v[40:41], 0, v[56:57]
	global_load_dword v17, v[42:43], off
	global_load_dword v35, v[44:45], off
	global_load_dword v37, v[46:47], off
	global_load_dword v58, v[48:49], off
	global_load_dword v59, v[50:51], off
	global_load_dword v60, v[52:53], off
	global_load_dword v61, v[54:55], off
	global_load_dword v62, v[56:57], off
	s_cbranch_execz .Ldry_cvA_real
.Ldry_cvA_c1:
	v_lshlrev_b64 v[42:43], 12, v[0:1]
	v_or_b32_e32 v0, 18, v38
	v_lshlrev_b64 v[44:45], 12, v[0:1]
	v_or_b32_e32 v0, 20, v38
	v_lshlrev_b64 v[46:47], 12, v[0:1]
	v_or_b32_e32 v0, 22, v38
	v_lshlrev_b64 v[48:49], 12, v[0:1]
	v_or_b32_e32 v0, 24, v38
	v_lshlrev_b64 v[50:51], 12, v[0:1]
	v_or_b32_e32 v0, 26, v38
	v_lshlrev_b64 v[52:53], 12, v[0:1]
	v_or_b32_e32 v0, 28, v38
	v_lshlrev_b64 v[54:55], 12, v[0:1]
	v_or_b32_e32 v0, 30, v38
	v_lshl_add_u64 v[42:43], v[40:41], 0, v[42:43]
	v_lshlrev_b64 v[56:57], 12, v[0:1]
	v_or_b32_e32 v0, 32, v38
	v_lshl_add_u64 v[44:45], v[40:41], 0, v[44:45]
	v_lshl_add_u64 v[46:47], v[40:41], 0, v[46:47]
	v_lshl_add_u64 v[48:49], v[40:41], 0, v[48:49]
	v_lshl_add_u64 v[50:51], v[40:41], 0, v[50:51]
	v_lshl_add_u64 v[52:53], v[40:41], 0, v[52:53]
	v_lshl_add_u64 v[54:55], v[40:41], 0, v[54:55]
	v_lshl_add_u64 v[56:57], v[40:41], 0, v[56:57]
	global_load_dword v63, v[42:43], off
	global_load_dword v64, v[44:45], off
	global_load_dword v65, v[46:47], off
	global_load_dword v66, v[48:49], off
	global_load_dword v67, v[50:51], off
	global_load_dword v68, v[52:53], off
	global_load_dword v69, v[54:55], off
	global_load_dword v70, v[56:57], off
	v_lshlrev_b64 v[42:43], 12, v[0:1]
	v_or_b32_e32 v0, 34, v38
	v_lshlrev_b64 v[44:45], 12, v[0:1]
	v_or_b32_e32 v0, 36, v38
	v_lshlrev_b64 v[46:47], 12, v[0:1]
	v_or_b32_e32 v0, 38, v38
	s_cbranch_execz .Ldry_cvA_real
.Ldry_cvA_c2:
	v_lshlrev_b64 v[48:49], 12, v[0:1]
	v_or_b32_e32 v0, 40, v38
	v_lshlrev_b64 v[50:51], 12, v[0:1]
	v_or_b32_e32 v0, 42, v38
	v_lshlrev_b64 v[52:53], 12, v[0:1]
	v_or_b32_e32 v0, 44, v38
	v_lshlrev_b64 v[54:55], 12, v[0:1]
	v_or_b32_e32 v0, 46, v38
	v_lshlrev_b64 v[56:57], 12, v[0:1]
	v_lshl_add_u64 v[42:43], v[40:41], 0, v[42:43]
	v_lshl_add_u64 v[56:57], v[40:41], 0, v[56:57]
	v_or_b32_e32 v0, 48, v38
	v_lshl_add_u64 v[44:45], v[40:41], 0, v[44:45]
	v_lshl_add_u64 v[46:47], v[40:41], 0, v[46:47]
	v_lshl_add_u64 v[48:49], v[40:41], 0, v[48:49]
	v_lshl_add_u64 v[50:51], v[40:41], 0, v[50:51]
	v_lshl_add_u64 v[52:53], v[40:41], 0, v[52:53]
	v_lshl_add_u64 v[54:55], v[40:41], 0, v[54:55]
	global_load_dword v71, v[42:43], off
	global_load_dword v72, v[44:45], off
	global_load_dword v73, v[46:47], off
	global_load_dword v74, v[48:49], off
	global_load_dword v75, v[50:51], off
	global_load_dword v76, v[52:53], off
	global_load_dword v77, v[54:55], off
	s_nop 0
	global_load_dword v56, v[56:57], off
	v_lshlrev_b64 v[42:43], 12, v[0:1]
	v_or_b32_e32 v0, 50, v38
	v_lshlrev_b64 v[44:45], 12, v[0:1]
	v_or_b32_e32 v0, 52, v38
	v_lshlrev_b64 v[46:47], 12, v[0:1]
	v_or_b32_e32 v0, 54, v38
	v_lshlrev_b64 v[48:49], 12, v[0:1]
	v_or_b32_e32 v0, 56, v38
	v_lshlrev_b64 v[50:51], 12, v[0:1]
	v_or_b32_e32 v0, 58, v38
	v_lshlrev_b64 v[52:53], 12, v[0:1]
	s_cbranch_execz .Ldry_cvA_real
; #define LAS __attribute__((address_space(3)))
; __device__ __forceinline__ unsigned pk2(float lo, float hi) { return f2bf(lo) | (f2bf(hi) << 16); }
; __device__ __forceinline__ void p0_transpose_kn(const float* W, int K, int N, bf16_t* WT, int row_off, LAS float* scr, int kb, int nb, int lane) {
;     ...
;     for (int i = 0; i < 32; ++i) wv[i] = W[(size_t)(k0 + 2 * i + (lane >> 5)) * N + n0 + (lane & 31)];
; #pragma unroll
;     for (int i = 0; i < 32; ++i) scr[(2 * i + (lane >> 5)) * 33 + (lane & 31)] = wv[i];
;     asm volatile("s_waitcnt lgkmcnt(0)" ::: "memory");
;     const int c = lane & 7;
; #pragma unroll
;     for (int j = 0; j < 4; ++j) { const int n = (lane >> 3) + 8 * j; const LAS float* s = scr + (8 * c) * 33 + n;
;         u32x4 o; o.x = pk2(s[0 * 33], s[1 * 33]); o.y = pk2(s[2 * 33], s[3 * 33]); o.z = pk2(s[4 * 33], s[5 * 33]); o.w = pk2(s[6 * 33], s[7 * 33]);
;         *(u32x4*)(WT + (size_t)(row_off + n0 + n) * K + k0 + 8 * c) = o; }
.Ldry_cvA_c3:
	v_or_b32_e32 v0, 60, v38
	v_lshlrev_b64 v[54:55], 12, v[0:1]
	v_or_b32_e32 v0, 62, v38
	v_lshlrev_b64 v[38:39], 12, v[0:1]
	v_lshl_add_u64 v[42:43], v[40:41], 0, v[42:43]
	v_lshl_add_u64 v[44:45], v[40:41], 0, v[44:45]
	v_lshl_add_u64 v[38:39], v[40:41], 0, v[38:39]
	v_lshl_add_u64 v[46:47], v[40:41], 0, v[46:47]
	v_lshl_add_u64 v[48:49], v[40:41], 0, v[48:49]
	v_lshl_add_u64 v[50:51], v[40:41], 0, v[50:51]
	v_lshl_add_u64 v[52:53], v[40:41], 0, v[52:53]
	v_lshl_add_u64 v[54:55], v[40:41], 0, v[54:55]
	global_load_dword v0, v[42:43], off
	global_load_dword v40, v[44:45], off
	global_load_dword v41, v[46:47], off
	s_nop 0
	global_load_dword v42, v[48:49], off
	global_load_dword v43, v[50:51], off
	global_load_dword v44, v[52:53], off
	global_load_dword v45, v[54:55], off
	s_nop 0
	global_load_dword v38, v[38:39], off
	s_waitcnt vmcnt(0)
	ds_write2_b32 v19, v17, v35 offset1:66
	ds_write2_b32 v19, v37, v58 offset0:132 offset1:198
	ds_write2_b32 v27, v59, v60 offset0:8 offset1:74
	ds_write2_b32 v27, v61, v62 offset0:140 offset1:206
	ds_write2_b32 v28, v63, v64 offset0:16 offset1:82
	ds_write2_b32 v28, v65, v66 offset0:148 offset1:214
	ds_write2_b32 v29, v67, v68 offset0:24 offset1:90
	ds_write2_b32 v29, v69, v70 offset0:156 offset1:222
	ds_write2_b32 v30, v71, v72 offset0:32 offset1:98
	ds_write2_b32 v30, v73, v74 offset0:164 offset1:230
	ds_write2_b32 v31, v75, v76 offset0:40 offset1:106
	ds_write2_b32 v31, v77, v56 offset0:172 offset1:238
	ds_write2_b32 v32, v0, v40 offset0:48 offset1:114
	ds_write2_b32 v32, v41, v42 offset0:180 offset1:246
	ds_write2_b32 v33, v43, v44 offset0:56 offset1:122
	s_cbranch_execz .Ldry_cvA_real
.Ldry_cvA_c4:
	ds_write2_b32 v33, v45, v38 offset0:188 offset1:254
	s_waitcnt lgkmcnt(0)
	ds_read2_b32 v[40:41], v21 offset1:8
	ds_read2_b32 v[44:45], v21 offset0:33 offset1:41
	ds_read2_b32 v[46:47], v21 offset0:66 offset1:74
	ds_read2_b32 v[48:49], v21 offset0:99 offset1:107
	ds_read2_b32 v[50:51], v21 offset0:132 offset1:140
	s_waitcnt lgkmcnt(4)
	v_bfe_u32 v0, v40, 16, 1
	v_add3_u32 v0, v40, v0, s19
	s_waitcnt lgkmcnt(3)
	v_bfe_u32 v17, v44, 16, 1
	v_mov_b32_e32 v37, v1
	v_lshrrev_b32_e32 v0, 16, v0
	v_add3_u32 v17, v44, v17, s19
	ds_read2_b32 v[52:53], v21 offset0:165 offset1:173
	v_lshl_add_u64 v[42:43], v[36:37], 1, v[4:5]
	v_and_or_b32 v36, v17, s20, v0
	s_waitcnt lgkmcnt(3)
	v_bfe_u32 v0, v46, 16, 1
	v_add3_u32 v0, v46, v0, s19
	s_waitcnt lgkmcnt(2)
	v_bfe_u32 v17, v48, 16, 1
	ds_read2_b32 v[54:55], v21 offset0:198 offset1:206
	v_lshrrev_b32_e32 v0, 16, v0
	v_add3_u32 v17, v48, v17, s19
	ds_read2_b32 v[56:57], v21 offset0:231 offset1:239
	v_and_or_b32 v37, v17, s20, v0
	s_waitcnt lgkmcnt(3)
	v_bfe_u32 v0, v50, 16, 1
	v_add3_u32 v0, v50, v0, s19
	s_waitcnt lgkmcnt(2)
	v_bfe_u32 v17, v52, 16, 1
	v_lshrrev_b32_e32 v0, 16, v0
	v_add3_u32 v17, v52, v17, s19
	v_and_or_b32 v38, v17, s20, v0
	s_waitcnt lgkmcnt(1)
	s_cbranch_execz .Ldry_cvA_real
.Ldry_cvA_c5:
	v_bfe_u32 v0, v54, 16, 1
	v_add3_u32 v0, v54, v0, s19
	s_waitcnt lgkmcnt(0)
	v_bfe_u32 v17, v56, 16, 1
	v_lshrrev_b32_e32 v0, 16, v0
	v_add3_u32 v17, v56, v17, s19
	v_and_or_b32 v39, v17, s20, v0
	v_or_b32_e32 v0, v16, v20
	v_lshlrev_b32_e32 v0, 11, v0
	v_lshl_add_u64 v[58:59], v[42:43], 0, v[0:1]
	v_bfe_u32 v0, v41, 16, 1
	v_add3_u32 v0, v41, v0, s19
	v_bfe_u32 v17, v45, 16, 1
	v_lshrrev_b32_e32 v0, 16, v0
	v_add3_u32 v17, v45, v17, s19
	global_store_dwordx4 v[58:59], v[36:39], off
	ds_read2_b32 v[40:41], v21 offset0:16 offset1:24
	s_nop 0
	v_and_or_b32 v36, v17, s20, v0
	v_bfe_u32 v0, v47, 16, 1
	v_add3_u32 v0, v47, v0, s19
	v_bfe_u32 v17, v49, 16, 1
	v_lshrrev_b32_e32 v0, 16, v0
	v_add3_u32 v17, v49, v17, s19
	v_and_or_b32 v37, v17, s20, v0
	v_bfe_u32 v0, v51, 16, 1
	v_add3_u32 v0, v51, v0, s19
	v_bfe_u32 v17, v53, 16, 1
	v_lshrrev_b32_e32 v0, 16, v0
	v_add3_u32 v17, v53, v17, s19
	v_and_or_b32 v38, v17, s20, v0
	v_bfe_u32 v0, v55, 16, 1
	v_add3_u32 v0, v55, v0, s19
	v_bfe_u32 v17, v57, 16, 1
	v_lshrrev_b32_e32 v0, 16, v0
	v_add3_u32 v17, v57, v17, s19
	v_and_or_b32 v39, v17, s20, v0
	v_or_b32_e32 v0, v16, v22
	s_cbranch_execz .Ldry_cvA_real
; #define LAS __attribute__((address_space(3)))
; __device__ __forceinline__ unsigned pk2(float lo, float hi) { return f2bf(lo) | (f2bf(hi) << 16); }
; __device__ __forceinline__ void p0_transpose_kn(const float* W, int K, int N, bf16_t* WT, int row_off, LAS float* scr, int kb, int nb, int lane) {
;     ...
;     for (int j = 0; j < 4; ++j) { const int n = (lane >> 3) + 8 * j; const LAS float* s = scr + (8 * c) * 33 + n;
;         u32x4 o; o.x = pk2(s[0 * 33], s[1 * 33]); o.y = pk2(s[2 * 33], s[3 * 33]); o.z = pk2(s[4 * 33], s[5 * 33]); o.w = pk2(s[6 * 33], s[7 * 33]);
;         *(u32x4*)(WT + (size_t)(row_off + n0 + n) * K + k0 + 8 * c) = o; }
;     asm volatile("s_waitcnt lgkmcnt(0)" ::: "memory");
; __global__ void __launch_bounds__(512, 2) mk_fwd(Args args) {
;     ...
;                 if (r < 16 * 128) { const int kb = r / 128, j = r % 128, sg = j >> 5, seg = sg == 0 ? 3 : sg + 6; p0_transpose_kn(w_in, 1024, 10240, Wt_in, 0, scr, kb, seg * 32 + (j & 31), lane); continue; } r -= 16 * 128;
;                 if (r < 512) { p0_transpose_kn(w_sb, 1024, 1024, Wt_sbhg, 0, scr, r / 32, r % 32, lane); continue; } r -= 512;
;                 if (r < 512) { p0_transpose_kn(w_hg, 1024, 1024, Wt_sbhg, 1024, scr, r / 32, r % 32, lane); continue; } r -= 512;
.Ldry_cvA_c6:
	v_lshlrev_b32_e32 v0, 11, v0
	v_lshl_add_u64 v[44:45], v[42:43], 0, v[0:1]
	global_store_dwordx4 v[44:45], v[36:39], off
	ds_read2_b32 v[44:45], v21 offset0:49 offset1:57
	ds_read2_b32 v[46:47], v21 offset0:82 offset1:90
	ds_read2_b32 v[48:49], v21 offset0:115 offset1:123
	s_waitcnt lgkmcnt(3)
	v_bfe_u32 v0, v40, 16, 1
	v_add3_u32 v0, v40, v0, s19
	s_waitcnt lgkmcnt(2)
	v_bfe_u32 v17, v44, 16, 1
	ds_read2_b32 v[50:51], v21 offset0:148 offset1:156
	v_lshrrev_b32_e32 v0, 16, v0
	v_add3_u32 v17, v44, v17, s19
	ds_read2_b32 v[52:53], v21 offset0:181 offset1:189
	v_and_or_b32 v36, v17, s20, v0
	s_waitcnt lgkmcnt(3)
	v_bfe_u32 v0, v46, 16, 1
	v_add3_u32 v0, v46, v0, s19
	s_waitcnt lgkmcnt(2)
	v_bfe_u32 v17, v48, 16, 1
	ds_read2_b32 v[54:55], v21 offset0:214 offset1:222
	v_lshrrev_b32_e32 v0, 16, v0
	v_add3_u32 v17, v48, v17, s19
	ds_read2_b32 v[56:57], v21 offset0:247 offset1:255
	v_and_or_b32 v37, v17, s20, v0
	s_waitcnt lgkmcnt(3)
	v_bfe_u32 v0, v50, 16, 1
	v_add3_u32 v0, v50, v0, s19
	s_waitcnt lgkmcnt(2)
	v_bfe_u32 v17, v52, 16, 1
	v_lshrrev_b32_e32 v0, 16, v0
	v_add3_u32 v17, v52, v17, s19
	v_and_or_b32 v38, v17, s20, v0
	s_waitcnt lgkmcnt(1)
	v_bfe_u32 v0, v54, 16, 1
	v_add3_u32 v0, v54, v0, s19
	s_waitcnt lgkmcnt(0)
	s_cbranch_execz .Ldry_cvA_real
.Ldry_cvA_c7:
	v_bfe_u32 v17, v56, 16, 1
	v_lshrrev_b32_e32 v0, 16, v0
	v_add3_u32 v17, v56, v17, s19
	v_and_or_b32 v39, v17, s20, v0
	v_or_b32_e32 v0, v16, v23
	v_lshlrev_b32_e32 v0, 11, v0
	v_lshl_add_u64 v[58:59], v[42:43], 0, v[0:1]
	v_bfe_u32 v0, v41, 16, 1
	v_add3_u32 v0, v41, v0, s19
	v_bfe_u32 v17, v45, 16, 1
	v_lshrrev_b32_e32 v0, 16, v0
	v_add3_u32 v17, v45, v17, s19
	global_store_dwordx4 v[58:59], v[36:39], off
	s_nop 1
	v_and_or_b32 v36, v17, s20, v0
	v_bfe_u32 v0, v47, 16, 1
	v_add3_u32 v0, v47, v0, s19
	v_bfe_u32 v17, v49, 16, 1
	v_lshrrev_b32_e32 v0, 16, v0
	v_add3_u32 v17, v49, v17, s19
	v_and_or_b32 v37, v17, s20, v0
	v_bfe_u32 v0, v51, 16, 1
	v_add3_u32 v0, v51, v0, s19
	v_bfe_u32 v17, v53, 16, 1
	v_lshrrev_b32_e32 v0, 16, v0
	v_add3_u32 v17, v53, v17, s19
	v_and_or_b32 v38, v17, s20, v0
	v_bfe_u32 v0, v55, 16, 1
	v_add3_u32 v0, v55, v0, s19
	v_bfe_u32 v17, v57, 16, 1
	v_lshrrev_b32_e32 v0, 16, v0
	v_add3_u32 v17, v57, v17, s19
	v_and_or_b32 v39, v17, s20, v0
	v_or_b32_e32 v0, v16, v24
	v_lshlrev_b32_e32 v0, 11, v0
	v_lshl_add_u64 v[16:17], v[42:43], 0, v[0:1]
	global_store_dwordx4 v[16:17], v[36:39], off
	s_waitcnt lgkmcnt(0)
	s_cbranch_execz .Ldry_cvA_real
.LBB0_407:
	s_andn2_saveexec_b64 s[12:13], s[12:13]
	s_cbranch_execz .LBB0_409
	v_readfirstlane_b32 s98, v200
	s_nop 0
	s_lshr_b32 s98, s98, 6
	s_cmp_eq_u32 s98, 0
	s_cbranch_scc1 .Ldry_cvB_real
	s_mov_b64 exec, 0
	s_cmp_eq_u32 s98, 1
	s_cbranch_scc1 .Ldry_cvB_c1
	s_cmp_eq_u32 s98, 2
	s_cbranch_scc1 .Ldry_cvB_c2
	s_cmp_eq_u32 s98, 3
	s_cbranch_scc1 .Ldry_cvB_c3
	s_cmp_eq_u32 s98, 4
	s_cbranch_scc1 .Ldry_cvB_c4
	s_cmp_eq_u32 s98, 5
	s_cbranch_scc1 .Ldry_cvB_c5
	s_cmp_eq_u32 s98, 6
	s_cbranch_scc1 .Ldry_cvB_c6
	s_branch .Ldry_cvB_c7
.Ldry_cvB_real:
	s_mov_b64 exec, -1
	v_and_b32_e32 v0, 0x1fc0, v25
	v_add_u32_e32 v36, 0xffffec00, v0
	v_or_b32_e32 v38, v36, v18
	v_lshlrev_b32_e32 v0, 2, v16
	v_lshl_add_u64 v[40:41], v[6:7], 0, v[0:1]
	v_or_b32_e32 v0, 2, v38
	v_lshlrev_b64 v[44:45], 12, v[0:1]
	v_or_b32_e32 v0, 4, v38
	v_lshlrev_b64 v[46:47], 12, v[0:1]
	v_or_b32_e32 v0, 6, v38
	v_lshlrev_b64 v[48:49], 12, v[0:1]
	v_or_b32_e32 v0, 8, v38
	v_lshlrev_b64 v[50:51], 12, v[0:1]
	v_or_b32_e32 v0, 10, v38
	v_mov_b32_e32 v39, v1
	v_lshlrev_b64 v[52:53], 12, v[0:1]
	v_or_b32_e32 v0, 12, v38
	v_lshlrev_b64 v[42:43], 12, v[38:39]
	v_lshlrev_b64 v[54:55], 12, v[0:1]
	v_or_b32_e32 v0, 14, v38
	v_lshl_add_u64 v[42:43], v[40:41], 0, v[42:43]
	v_lshlrev_b64 v[56:57], 12, v[0:1]
	v_or_b32_e32 v0, 16, v38
	v_lshl_add_u64 v[44:45], v[40:41], 0, v[44:45]
	v_lshl_add_u64 v[46:47], v[40:41], 0, v[46:47]
	v_lshl_add_u64 v[48:49], v[40:41], 0, v[48:49]
	v_lshl_add_u64 v[50:51], v[40:41], 0, v[50:51]
	v_lshl_add_u64 v[52:53], v[40:41], 0, v[52:53]
	v_lshl_add_u64 v[54:55], v[40:41], 0, v[54:55]
	v_lshl_add_u64 v[56:57], v[40:41], 0, v[56:57]
	global_load_dword v17, v[42:43], off
	global_load_dword v35, v[44:45], off
	global_load_dword v37, v[46:47], off
	global_load_dword v58, v[48:49], off
	global_load_dword v59, v[50:51], off
	global_load_dword v60, v[52:53], off
	global_load_dword v61, v[54:55], off
	global_load_dword v62, v[56:57], off
	s_cbranch_execz .Ldry_cvB_real

; #define LAS __attribute__((address_space(3)))
; __device__ __forceinline__ unsigned pk2(float lo, float hi) { return f2bf(lo) | (f2bf(hi) << 16); }
; __device__ __forceinline__ void p0_transpose_kn(const float* W, int K, int N, bf16_t* WT, int row_off, LAS float* scr, int kb, int nb, int lane) {
;     ...
;     for (int i = 0; i < 32; ++i) wv[i] = W[(size_t)(k0 + 2 * i + (lane >> 5)) * N + n0 + (lane & 31)];
; #pragma unroll
;     for (int i = 0; i < 32; ++i) scr[(2 * i + (lane >> 5)) * 33 + (lane & 31)] = wv[i];
;     asm volatile("s_waitcnt lgkmcnt(0)" ::: "memory");
;     const int c = lane & 7;
; #pragma unroll
;     for (int j = 0; j < 4; ++j) { const int n = (lane >> 3) + 8 * j; const LAS float* s = scr + (8 * c) * 33 + n;
;         u32x4 o; o.x = pk2(s[0 * 33], s[1 * 33]); o.y = pk2(s[2 * 33], s[3 * 33]); o.z = pk2(s[4 * 33], s[5 * 33]); o.w = pk2(s[6 * 33], s[7 * 33]);
;         *(u32x4*)(WT + (size_t)(row_off + n0 + n) * K + k0 + 8 * c) = o; }
.Ldry_cvB_c2:
	v_lshlrev_b64 v[48:49], 12, v[0:1]
	v_or_b32_e32 v0, 40, v38
	v_lshlrev_b64 v[50:51], 12, v[0:1]
	v_or_b32_e32 v0, 42, v38
	v_lshlrev_b64 v[52:53], 12, v[0:1]
	v_or_b32_e32 v0, 44, v38
	v_lshlrev_b64 v[54:55], 12, v[0:1]
	v_or_b32_e32 v0, 46, v38
	v_lshlrev_b64 v[56:57], 12, v[0:1]
	v_lshl_add_u64 v[42:43], v[40:41], 0, v[42:43]
	v_lshl_add_u64 v[56:57], v[40:41], 0, v[56:57]
	v_or_b32_e32 v0, 48, v38
	v_lshl_add_u64 v[44:45], v[40:41], 0, v[44:45]
	v_lshl_add_u64 v[46:47], v[40:41], 0, v[46:47]
	v_lshl_add_u64 v[48:49], v[40:41], 0, v[48:49]
	v_lshl_add_u64 v[50:51], v[40:41], 0, v[50:51]
	v_lshl_add_u64 v[52:53], v[40:41], 0, v[52:53]
	v_lshl_add_u64 v[54:55], v[40:41], 0, v[54:55]
	global_load_dword v71, v[42:43], off
	global_load_dword v72, v[44:45], off
	global_load_dword v73, v[46:47], off
	global_load_dword v74, v[48:49], off
	global_load_dword v75, v[50:51], off
	global_load_dword v76, v[52:53], off
	global_load_dword v77, v[54:55], off
	s_nop 0
	global_load_dword v56, v[56:57], off
	v_lshlrev_b64 v[42:43], 12, v[0:1]
	v_or_b32_e32 v0, 50, v38
	v_lshlrev_b64 v[44:45], 12, v[0:1]
	v_or_b32_e32 v0, 52, v38
	v_lshlrev_b64 v[46:47], 12, v[0:1]
	v_or_b32_e32 v0, 54, v38
	v_lshlrev_b64 v[48:49], 12, v[0:1]
	v_or_b32_e32 v0, 56, v38
	v_lshlrev_b64 v[50:51], 12, v[0:1]
	v_or_b32_e32 v0, 58, v38
	s_cbranch_execz .Ldry_cvB_real
.Ldry_cvB_c3:
	v_lshlrev_b64 v[52:53], 12, v[0:1]
	v_or_b32_e32 v0, 60, v38
	v_lshlrev_b64 v[54:55], 12, v[0:1]
	v_or_b32_e32 v0, 62, v38
	v_lshlrev_b64 v[38:39], 12, v[0:1]
	v_lshl_add_u64 v[42:43], v[40:41], 0, v[42:43]
	v_lshl_add_u64 v[44:45], v[40:41], 0, v[44:45]
	v_lshl_add_u64 v[38:39], v[40:41], 0, v[38:39]
	v_lshl_add_u64 v[46:47], v[40:41], 0, v[46:47]
	v_lshl_add_u64 v[48:49], v[40:41], 0, v[48:49]
	v_lshl_add_u64 v[50:51], v[40:41], 0, v[50:51]
	v_lshl_add_u64 v[52:53], v[40:41], 0, v[52:53]
	v_lshl_add_u64 v[54:55], v[40:41], 0, v[54:55]
	global_load_dword v0, v[42:43], off
	global_load_dword v40, v[44:45], off
	global_load_dword v41, v[46:47], off
	s_nop 0
	global_load_dword v42, v[48:49], off
	global_load_dword v43, v[50:51], off
	global_load_dword v44, v[52:53], off
	global_load_dword v45, v[54:55], off
	s_nop 0
	global_load_dword v38, v[38:39], off
	s_waitcnt vmcnt(0)
	ds_write2_b32 v19, v17, v35 offset1:66
	ds_write2_b32 v19, v37, v58 offset0:132 offset1:198
	ds_write2_b32 v27, v59, v60 offset0:8 offset1:74
	ds_write2_b32 v27, v61, v62 offset0:140 offset1:206
	ds_write2_b32 v28, v63, v64 offset0:16 offset1:82
	ds_write2_b32 v28, v65, v66 offset0:148 offset1:214
	ds_write2_b32 v29, v67, v68 offset0:24 offset1:90
	ds_write2_b32 v29, v69, v70 offset0:156 offset1:222
	ds_write2_b32 v30, v71, v72 offset0:32 offset1:98
	ds_write2_b32 v30, v73, v74 offset0:164 offset1:230
	ds_write2_b32 v31, v75, v76 offset0:40 offset1:106
	ds_write2_b32 v31, v77, v56 offset0:172 offset1:238
	ds_write2_b32 v32, v0, v40 offset0:48 offset1:114
	ds_write2_b32 v32, v41, v42 offset0:180 offset1:246
	s_cbranch_execz .Ldry_cvB_real
.Ldry_cvB_c4:
	ds_write2_b32 v33, v43, v44 offset0:56 offset1:122
	ds_write2_b32 v33, v45, v38 offset0:188 offset1:254
	s_waitcnt lgkmcnt(0)
	ds_read2_b32 v[40:41], v21 offset1:8
	ds_read2_b32 v[42:43], v21 offset0:33 offset1:41
	ds_read2_b32 v[44:45], v21 offset0:66 offset1:74
	ds_read2_b32 v[46:47], v21 offset0:99 offset1:107
	v_mov_b32_e32 v37, v1
	s_waitcnt lgkmcnt(3)
	v_bfe_u32 v0, v40, 16, 1
	v_or_b32_e32 v35, 0x400, v16
	v_lshl_add_u64 v[16:17], v[36:37], 1, v[8:9]
	v_add3_u32 v0, v40, v0, s19
	s_waitcnt lgkmcnt(2)
	v_bfe_u32 v36, v42, 16, 1
	ds_read2_b32 v[48:49], v21 offset0:132 offset1:140
	v_lshrrev_b32_e32 v0, 16, v0
	v_add3_u32 v36, v42, v36, s19
	ds_read2_b32 v[50:51], v21 offset0:165 offset1:173
	v_and_or_b32 v36, v36, s20, v0
	s_waitcnt lgkmcnt(3)
	v_bfe_u32 v0, v44, 16, 1
	v_add3_u32 v0, v44, v0, s19
	s_waitcnt lgkmcnt(2)
	v_bfe_u32 v37, v46, 16, 1
	ds_read2_b32 v[52:53], v21 offset0:198 offset1:206
	v_lshrrev_b32_e32 v0, 16, v0
	v_add3_u32 v37, v46, v37, s19
	ds_read2_b32 v[54:55], v21 offset0:231 offset1:239
	v_and_or_b32 v37, v37, s20, v0
	s_waitcnt lgkmcnt(3)
	v_bfe_u32 v0, v48, 16, 1
	v_add3_u32 v0, v48, v0, s19
	s_waitcnt lgkmcnt(2)
	v_bfe_u32 v38, v50, 16, 1
	v_lshrrev_b32_e32 v0, 16, v0
	v_add3_u32 v38, v50, v38, s19
	v_and_or_b32 v38, v38, s20, v0
	s_cbranch_execz .Ldry_cvB_real
; #define LAS __attribute__((address_space(3)))
; __device__ __forceinline__ unsigned pk2(float lo, float hi) { return f2bf(lo) | (f2bf(hi) << 16); }
; __device__ __forceinline__ void p0_transpose_kn(const float* W, int K, int N, bf16_t* WT, int row_off, LAS float* scr, int kb, int nb, int lane) {
;     ...
;     const int c = lane & 7;
; #pragma unroll
;     for (int j = 0; j < 4; ++j) { const int n = (lane >> 3) + 8 * j; const LAS float* s = scr + (8 * c) * 33 + n;
;         u32x4 o; o.x = pk2(s[0 * 33], s[1 * 33]); o.y = pk2(s[2 * 33], s[3 * 33]); o.z = pk2(s[4 * 33], s[5 * 33]); o.w = pk2(s[6 * 33], s[7 * 33]);
;         *(u32x4*)(WT + (size_t)(row_off + n0 + n) * K + k0 + 8 * c) = o; }
;     asm volatile("s_waitcnt lgkmcnt(0)" ::: "memory");
.Ldry_cvB_c5:
	s_waitcnt lgkmcnt(1)
	v_bfe_u32 v0, v52, 16, 1
	v_add3_u32 v0, v52, v0, s19
	s_waitcnt lgkmcnt(0)
	v_bfe_u32 v39, v54, 16, 1
	v_lshrrev_b32_e32 v0, 16, v0
	v_add3_u32 v39, v54, v39, s19
	v_and_or_b32 v39, v39, s20, v0
	v_or_b32_e32 v0, v35, v20
	v_lshlrev_b32_e32 v0, 11, v0
	v_lshl_add_u64 v[56:57], v[16:17], 0, v[0:1]
	v_bfe_u32 v0, v41, 16, 1
	global_store_dwordx4 v[56:57], v[36:39], off
	v_add3_u32 v0, v41, v0, s19
	v_lshrrev_b32_e32 v0, 16, v0
	v_bfe_u32 v36, v43, 16, 1
	v_add3_u32 v36, v43, v36, s19
	v_and_or_b32 v36, v36, s20, v0
	v_bfe_u32 v0, v45, 16, 1
	v_add3_u32 v0, v45, v0, s19
	v_bfe_u32 v37, v47, 16, 1
	v_lshrrev_b32_e32 v0, 16, v0
	v_add3_u32 v37, v47, v37, s19
	v_and_or_b32 v37, v37, s20, v0
	v_bfe_u32 v0, v49, 16, 1
	v_add3_u32 v0, v49, v0, s19
	v_bfe_u32 v38, v51, 16, 1
	v_lshrrev_b32_e32 v0, 16, v0
	v_add3_u32 v38, v51, v38, s19
	v_and_or_b32 v38, v38, s20, v0
	v_bfe_u32 v0, v53, 16, 1
	v_add3_u32 v0, v53, v0, s19
	v_bfe_u32 v39, v55, 16, 1
	v_lshrrev_b32_e32 v0, 16, v0
	v_add3_u32 v39, v55, v39, s19
	v_and_or_b32 v39, v39, s20, v0
	v_or_b32_e32 v0, v35, v22
	s_cbranch_execz .Ldry_cvB_real
.Ldry_cvB_c6:
	v_lshlrev_b32_e32 v0, 11, v0
	ds_read2_b32 v[40:41], v21 offset0:16 offset1:24
	v_lshl_add_u64 v[42:43], v[16:17], 0, v[0:1]
	global_store_dwordx4 v[42:43], v[36:39], off
	ds_read2_b32 v[42:43], v21 offset0:49 offset1:57
	ds_read2_b32 v[44:45], v21 offset0:82 offset1:90
	ds_read2_b32 v[46:47], v21 offset0:115 offset1:123
	s_waitcnt lgkmcnt(3)
	v_bfe_u32 v0, v40, 16, 1
	v_add3_u32 v0, v40, v0, s19
	s_waitcnt lgkmcnt(2)
	v_bfe_u32 v36, v42, 16, 1
	ds_read2_b32 v[48:49], v21 offset0:148 offset1:156
	v_lshrrev_b32_e32 v0, 16, v0
	v_add3_u32 v36, v42, v36, s19
	ds_read2_b32 v[50:51], v21 offset0:181 offset1:189
	v_and_or_b32 v36, v36, s20, v0
	s_waitcnt lgkmcnt(3)
	v_bfe_u32 v0, v44, 16, 1
	v_add3_u32 v0, v44, v0, s19
	s_waitcnt lgkmcnt(2)
	v_bfe_u32 v37, v46, 16, 1
	ds_read2_b32 v[52:53], v21 offset0:214 offset1:222
	v_lshrrev_b32_e32 v0, 16, v0
	v_add3_u32 v37, v46, v37, s19
	ds_read2_b32 v[54:55], v21 offset0:247 offset1:255
	v_and_or_b32 v37, v37, s20, v0
	s_waitcnt lgkmcnt(3)
	v_bfe_u32 v0, v48, 16, 1
	v_add3_u32 v0, v48, v0, s19
	s_waitcnt lgkmcnt(2)
	v_bfe_u32 v38, v50, 16, 1
	v_lshrrev_b32_e32 v0, 16, v0
	v_add3_u32 v38, v50, v38, s19
	v_and_or_b32 v38, v38, s20, v0
	s_waitcnt lgkmcnt(1)
	v_bfe_u32 v0, v52, 16, 1
	v_add3_u32 v0, v52, v0, s19
	s_cbranch_execz .Ldry_cvB_real
.Ldry_cvB_c7:
	s_waitcnt lgkmcnt(0)
	v_bfe_u32 v39, v54, 16, 1
	v_lshrrev_b32_e32 v0, 16, v0
	v_add3_u32 v39, v54, v39, s19
	v_and_or_b32 v39, v39, s20, v0
	v_or_b32_e32 v0, v35, v23
	v_lshlrev_b32_e32 v0, 11, v0
	v_lshl_add_u64 v[56:57], v[16:17], 0, v[0:1]
	v_bfe_u32 v0, v41, 16, 1
	global_store_dwordx4 v[56:57], v[36:39], off
	v_add3_u32 v0, v41, v0, s19
	v_lshrrev_b32_e32 v0, 16, v0
	v_bfe_u32 v36, v43, 16, 1
	v_add3_u32 v36, v43, v36, s19
	v_and_or_b32 v36, v36, s20, v0
	v_bfe_u32 v0, v45, 16, 1
	v_add3_u32 v0, v45, v0, s19
	v_bfe_u32 v37, v47, 16, 1
	v_lshrrev_b32_e32 v0, 16, v0
	v_add3_u32 v37, v47, v37, s19
	v_and_or_b32 v37, v37, s20, v0
	v_bfe_u32 v0, v49, 16, 1
	v_add3_u32 v0, v49, v0, s19
	v_bfe_u32 v38, v51, 16, 1
	v_lshrrev_b32_e32 v0, 16, v0
	v_add3_u32 v38, v51, v38, s19
	v_and_or_b32 v38, v38, s20, v0
	v_bfe_u32 v0, v53, 16, 1
	v_add3_u32 v0, v53, v0, s19
	v_bfe_u32 v39, v55, 16, 1
	v_lshrrev_b32_e32 v0, 16, v0
	v_add3_u32 v39, v55, v39, s19
	v_and_or_b32 v39, v39, s20, v0
	v_or_b32_e32 v0, v35, v24
	v_lshlrev_b32_e32 v0, 11, v0
	v_lshl_add_u64 v[16:17], v[16:17], 0, v[0:1]
	global_store_dwordx4 v[16:17], v[36:39], off
	s_waitcnt lgkmcnt(0)
	s_cbranch_execz .Ldry_cvB_real

; #define LAS __attribute__((address_space(3)))
; __device__ __forceinline__ void p0_transpose_kn(const float* W, int K, int N, bf16_t* WT, int row_off, LAS float* scr, int kb, int nb, int lane) {
;     const int k0 = 64 * kb, n0 = 32 * nb;
;     float wv[32];
; #pragma unroll
;     for (int i = 0; i < 32; ++i) wv[i] = W[(size_t)(k0 + 2 * i + (lane >> 5)) * N + n0 + (lane & 31)];
; __global__ void __launch_bounds__(512, 2) mk_fwd(Args args) {
;     ...
;                 if (r < 16 * 128) { const int kb = r / 128, j = r % 128, sg = j >> 5, seg = sg == 0 ? 3 : sg + 6; p0_transpose_kn(w_in, 1024, 10240, Wt_in, 0, scr, kb, seg * 32 + (j & 31), lane); continue; } r -= 16 * 128;
;                 if (r < 512) { p0_transpose_kn(w_sb, 1024, 1024, Wt_sbhg, 0, scr, r / 32, r % 32, lane); continue; } r -= 512;
.LBB0_410:
	s_andn2_saveexec_b64 s[10:11], s[10:11]
	s_cbranch_execz .LBB0_412
	v_readfirstlane_b32 s98, v200
	s_nop 0
	s_lshr_b32 s98, s98, 6
	s_cmp_eq_u32 s98, 0
	s_cbranch_scc1 .Ldry_cvC_real
	s_mov_b64 exec, 0
	s_cmp_eq_u32 s98, 1
	s_cbranch_scc1 .Ldry_cvC_c1
	s_cmp_eq_u32 s98, 2
	s_cbranch_scc1 .Ldry_cvC_c2
	s_cmp_eq_u32 s98, 3
	s_cbranch_scc1 .Ldry_cvC_c3
	s_cmp_eq_u32 s98, 4
	s_cbranch_scc1 .Ldry_cvC_c4
	s_cmp_eq_u32 s98, 5
	s_cbranch_scc1 .Ldry_cvC_c5
	s_cmp_eq_u32 s98, 6
	s_cbranch_scc1 .Ldry_cvC_c6
	s_branch .Ldry_cvC_c7
.Ldry_cvC_real:
	s_mov_b64 exec, -1
	v_and_b32_e32 v0, 0x1fc0, v25
	v_add_u32_e32 v36, 0xfffff000, v0
	v_or_b32_e32 v38, v36, v18
	v_lshlrev_b32_e32 v0, 2, v16
	v_lshl_add_u64 v[40:41], v[10:11], 0, v[0:1]
	v_or_b32_e32 v0, 2, v38
	v_lshlrev_b64 v[44:45], 12, v[0:1]
	v_or_b32_e32 v0, 4, v38
	v_lshlrev_b64 v[46:47], 12, v[0:1]
	v_or_b32_e32 v0, 6, v38
	v_lshlrev_b64 v[48:49], 12, v[0:1]
	v_or_b32_e32 v0, 8, v38
	v_lshlrev_b64 v[50:51], 12, v[0:1]
	v_or_b32_e32 v0, 10, v38
	v_mov_b32_e32 v39, v1
	v_lshlrev_b64 v[52:53], 12, v[0:1]
	v_or_b32_e32 v0, 12, v38
	v_lshlrev_b64 v[42:43], 12, v[38:39]
	v_lshlrev_b64 v[54:55], 12, v[0:1]
	v_or_b32_e32 v0, 14, v38
	v_lshl_add_u64 v[42:43], v[40:41], 0, v[42:43]
	v_lshlrev_b64 v[56:57], 12, v[0:1]
	v_or_b32_e32 v0, 16, v38
	v_lshl_add_u64 v[44:45], v[40:41], 0, v[44:45]
	v_lshl_add_u64 v[46:47], v[40:41], 0, v[46:47]
	v_lshl_add_u64 v[48:49], v[40:41], 0, v[48:49]
	v_lshl_add_u64 v[50:51], v[40:41], 0, v[50:51]
	v_lshl_add_u64 v[52:53], v[40:41], 0, v[52:53]
	v_lshl_add_u64 v[54:55], v[40:41], 0, v[54:55]
	v_lshl_add_u64 v[56:57], v[40:41], 0, v[56:57]
	global_load_dword v17, v[42:43], off
	global_load_dword v35, v[44:45], off
	global_load_dword v37, v[46:47], off
	global_load_dword v58, v[48:49], off
	global_load_dword v59, v[50:51], off
	global_load_dword v60, v[52:53], off
	global_load_dword v61, v[54:55], off
	global_load_dword v62, v[56:57], off
	s_cbranch_execz .Ldry_cvC_real

; #define LAS __attribute__((address_space(3)))
; __device__ __forceinline__ unsigned pk2(float lo, float hi) { return f2bf(lo) | (f2bf(hi) << 16); }
; __device__ __forceinline__ void p0_transpose_kn(const float* W, int K, int N, bf16_t* WT, int row_off, LAS float* scr, int kb, int nb, int lane) {
;     ...
;     for (int i = 0; i < 32; ++i) scr[(2 * i + (lane >> 5)) * 33 + (lane & 31)] = wv[i];
;     asm volatile("s_waitcnt lgkmcnt(0)" ::: "memory");
;     const int c = lane & 7;
; #pragma unroll
;     for (int j = 0; j < 4; ++j) { const int n = (lane >> 3) + 8 * j; const LAS float* s = scr + (8 * c) * 33 + n;
;         u32x4 o; o.x = pk2(s[0 * 33], s[1 * 33]); o.y = pk2(s[2 * 33], s[3 * 33]); o.z = pk2(s[4 * 33], s[5 * 33]); o.w = pk2(s[6 * 33], s[7 * 33]);
;         *(u32x4*)(WT + (size_t)(row_off + n0 + n) * K + k0 + 8 * c) = o; }
.Ldry_cvC_c4:
	ds_write2_b32 v33, v45, v38 offset0:188 offset1:254
	s_waitcnt lgkmcnt(0)
	ds_read2_b32 v[40:41], v21 offset1:8
	ds_read2_b32 v[44:45], v21 offset0:33 offset1:41
	ds_read2_b32 v[46:47], v21 offset0:66 offset1:74
	ds_read2_b32 v[48:49], v21 offset0:99 offset1:107
	ds_read2_b32 v[50:51], v21 offset0:132 offset1:140
	s_waitcnt lgkmcnt(4)
	v_bfe_u32 v0, v40, 16, 1
	v_add3_u32 v0, v40, v0, s19
	s_waitcnt lgkmcnt(3)
	v_bfe_u32 v17, v44, 16, 1
	v_mov_b32_e32 v37, v1
	v_lshrrev_b32_e32 v0, 16, v0
	v_add3_u32 v17, v44, v17, s19
	ds_read2_b32 v[52:53], v21 offset0:165 offset1:173
	v_lshl_add_u64 v[42:43], v[36:37], 1, v[8:9]
	v_and_or_b32 v36, v17, s20, v0
	s_waitcnt lgkmcnt(3)
	v_bfe_u32 v0, v46, 16, 1
	v_add3_u32 v0, v46, v0, s19
	s_waitcnt lgkmcnt(2)
	v_bfe_u32 v17, v48, 16, 1
	ds_read2_b32 v[54:55], v21 offset0:198 offset1:206
	v_lshrrev_b32_e32 v0, 16, v0
	v_add3_u32 v17, v48, v17, s19
	ds_read2_b32 v[56:57], v21 offset0:231 offset1:239
	v_and_or_b32 v37, v17, s20, v0
	s_waitcnt lgkmcnt(3)
	v_bfe_u32 v0, v50, 16, 1
	v_add3_u32 v0, v50, v0, s19
	s_waitcnt lgkmcnt(2)
	v_bfe_u32 v17, v52, 16, 1
	v_lshrrev_b32_e32 v0, 16, v0
	v_add3_u32 v17, v52, v17, s19
	v_and_or_b32 v38, v17, s20, v0
	s_waitcnt lgkmcnt(1)
	s_cbranch_execz .Ldry_cvC_real

; #define LAS __attribute__((address_space(3)))
; __device__ __forceinline__ void p0_transpose_kn(const float* W, int K, int N, bf16_t* WT, int row_off, LAS float* scr, int kb, int nb, int lane) {
;     const int k0 = 64 * kb, n0 = 32 * nb;
;     float wv[32];
; #pragma unroll
;     for (int i = 0; i < 32; ++i) wv[i] = W[(size_t)(k0 + 2 * i + (lane >> 5)) * N + n0 + (lane & 31)];
; #pragma unroll
;     for (int i = 0; i < 32; ++i) scr[(2 * i + (lane >> 5)) * 33 + (lane & 31)] = wv[i];
; __global__ void __launch_bounds__(512, 2) mk_fwd(Args args) {
;     ...
;             for (int it = gw; it < 16 * 128 + 3 * 512; it += NGW) {
;                 int r = it;
;                 if (r < 16 * 128) { const int kb = r / 128, j = r % 128, sg = j >> 5, seg = sg == 0 ? 3 : sg + 6; p0_transpose_kn(w_in, 1024, 10240, Wt_in, 0, scr, kb, seg * 32 + (j & 31), lane); continue; } r -= 16 * 128;
.LBB0_413:
	s_andn2_saveexec_b64 s[8:9], s[8:9]
	s_cbranch_execz .LBB0_402
	v_readfirstlane_b32 s98, v200
	s_nop 0
	s_lshr_b32 s98, s98, 6
	s_cmp_eq_u32 s98, 0
	s_cbranch_scc1 .Ldry_cvD_real
	s_mov_b64 exec, 0
	s_cmp_eq_u32 s98, 1
	s_cbranch_scc1 .Ldry_cvD_c1
	s_cmp_eq_u32 s98, 2
	s_cbranch_scc1 .Ldry_cvD_c2
	s_cmp_eq_u32 s98, 3
	s_cbranch_scc1 .Ldry_cvD_c3
	s_cmp_eq_u32 s98, 4
	s_cbranch_scc1 .Ldry_cvD_c4
	s_cmp_eq_u32 s98, 5
	s_cbranch_scc1 .Ldry_cvD_c5
	s_cmp_eq_u32 s98, 6
	s_cbranch_scc1 .Ldry_cvD_c6
	s_branch .Ldry_cvD_c7
.Ldry_cvD_real:
	s_mov_b64 exec, -1
	v_ashrrev_i32_e32 v0, 31, v169
	v_lshrrev_b32_e32 v0, 25, v0
	v_add_u32_e32 v0, v169, v0
	v_ashrrev_i32_e32 v16, 7, v0
	v_and_b32_e32 v0, 0xffffff80, v0
	v_sub_u32_e32 v0, v169, v0
	v_and_b32_e32 v17, 0x7ffffe0, v0
	v_add_u32_e32 v17, 0xc0, v17
	v_cmp_lt_u32_e32 vcc, 31, v0
	v_lshlrev_b32_e32 v36, 6, v16
	s_nop 0
	v_cndmask_b32_e32 v17, v34, v17, vcc
	v_and_or_b32 v0, v0, 31, v17
	v_lshlrev_b32_e32 v16, 5, v0
	v_or_b32_e32 v0, v36, v18
	v_ashrrev_i32_e32 v17, 31, v16
	v_lshl_add_u64 v[38:39], v[16:17], 2, v[12:13]
	v_or_b32_e32 v17, 2, v0
	v_mad_i64_i32 v[42:43], s[10:11], v17, s21, v[38:39]
	v_or_b32_e32 v17, 4, v0
	v_mad_i64_i32 v[44:45], s[10:11], v17, s21, v[38:39]
	v_or_b32_e32 v17, 6, v0
	v_mad_i64_i32 v[46:47], s[10:11], v17, s21, v[38:39]
	v_or_b32_e32 v17, 8, v0
	v_mad_i64_i32 v[48:49], s[10:11], v17, s21, v[38:39]
	v_or_b32_e32 v17, 10, v0
	v_mad_i64_i32 v[50:51], s[10:11], v17, s21, v[38:39]
	v_or_b32_e32 v17, 12, v0
	v_mad_i64_i32 v[52:53], s[10:11], v17, s21, v[38:39]
	v_or_b32_e32 v17, 14, v0
	v_mad_i64_i32 v[40:41], s[10:11], v0, s21, v[38:39]
	v_mad_i64_i32 v[54:55], s[10:11], v17, s21, v[38:39]
	global_load_dword v17, v[40:41], off
	global_load_dword v35, v[42:43], off
	global_load_dword v37, v[44:45], off
	global_load_dword v56, v[46:47], off
	s_cbranch_execz .Ldry_cvD_real
.Ldry_cvD_c1:
	global_load_dword v57, v[48:49], off
	global_load_dword v58, v[50:51], off
	global_load_dword v59, v[52:53], off
	global_load_dword v60, v[54:55], off
	v_or_b32_e32 v40, 16, v0
	v_or_b32_e32 v42, 18, v0
	v_or_b32_e32 v44, 20, v0
	v_or_b32_e32 v46, 22, v0
	v_or_b32_e32 v48, 24, v0
	v_or_b32_e32 v50, 26, v0
	v_or_b32_e32 v52, 28, v0
	v_or_b32_e32 v54, 30, v0
	v_mad_i64_i32 v[40:41], s[10:11], v40, s21, v[38:39]
	v_mad_i64_i32 v[42:43], s[10:11], v42, s21, v[38:39]
	v_mad_i64_i32 v[44:45], s[10:11], v44, s21, v[38:39]
	v_mad_i64_i32 v[46:47], s[10:11], v46, s21, v[38:39]
	v_mad_i64_i32 v[48:49], s[10:11], v48, s21, v[38:39]
	v_mad_i64_i32 v[50:51], s[10:11], v50, s21, v[38:39]
	v_mad_i64_i32 v[52:53], s[10:11], v52, s21, v[38:39]
	v_mad_i64_i32 v[54:55], s[10:11], v54, s21, v[38:39]
	global_load_dword v61, v[40:41], off
	global_load_dword v62, v[42:43], off
	global_load_dword v63, v[44:45], off
	global_load_dword v64, v[46:47], off
	global_load_dword v65, v[48:49], off
	global_load_dword v66, v[50:51], off
	global_load_dword v67, v[52:53], off
	global_load_dword v68, v[54:55], off
	v_or_b32_e32 v40, 32, v0
	v_or_b32_e32 v42, 34, v0
	v_or_b32_e32 v44, 36, v0
	v_or_b32_e32 v46, 38, v0
	v_or_b32_e32 v48, 40, v0
	v_or_b32_e32 v50, 42, v0
	v_or_b32_e32 v52, 44, v0
	v_or_b32_e32 v54, 46, v0
	s_cbranch_execz .Ldry_cvD_real
.Ldry_cvD_c2:
	v_mad_i64_i32 v[40:41], s[10:11], v40, s21, v[38:39]
	v_mad_i64_i32 v[42:43], s[10:11], v42, s21, v[38:39]
	v_mad_i64_i32 v[44:45], s[10:11], v44, s21, v[38:39]
	v_mad_i64_i32 v[46:47], s[10:11], v46, s21, v[38:39]
	v_mad_i64_i32 v[48:49], s[10:11], v48, s21, v[38:39]
	v_mad_i64_i32 v[50:51], s[10:11], v50, s21, v[38:39]
	v_mad_i64_i32 v[52:53], s[10:11], v52, s21, v[38:39]
	v_mad_i64_i32 v[54:55], s[10:11], v54, s21, v[38:39]
	global_load_dword v69, v[40:41], off
	global_load_dword v70, v[42:43], off
	global_load_dword v71, v[44:45], off
	global_load_dword v72, v[46:47], off
	global_load_dword v73, v[48:49], off
	global_load_dword v74, v[50:51], off
	global_load_dword v75, v[52:53], off
	s_nop 0
	global_load_dword v54, v[54:55], off
	v_or_b32_e32 v40, 48, v0
	v_or_b32_e32 v42, 50, v0
	v_or_b32_e32 v44, 52, v0
	v_or_b32_e32 v46, 54, v0
	v_or_b32_e32 v48, 56, v0
	v_or_b32_e32 v50, 58, v0
	v_or_b32_e32 v52, 60, v0
	v_or_b32_e32 v0, 62, v0
	v_mad_i64_i32 v[40:41], s[10:11], v40, s21, v[38:39]
	v_mad_i64_i32 v[42:43], s[10:11], v42, s21, v[38:39]
	v_mad_i64_i32 v[44:45], s[10:11], v44, s21, v[38:39]
	v_mad_i64_i32 v[46:47], s[10:11], v46, s21, v[38:39]
	v_mad_i64_i32 v[48:49], s[10:11], v48, s21, v[38:39]
	v_mad_i64_i32 v[50:51], s[10:11], v50, s21, v[38:39]
	v_mad_i64_i32 v[52:53], s[10:11], v52, s21, v[38:39]
	v_mad_i64_i32 v[38:39], s[10:11], v0, s21, v[38:39]
	global_load_dword v0, v[40:41], off
	s_nop 0
	s_cbranch_execz .Ldry_cvD_real
; #define LAS __attribute__((address_space(3)))
; __device__ __forceinline__ unsigned pk2(float lo, float hi) { return f2bf(lo) | (f2bf(hi) << 16); }
; __device__ __forceinline__ void p0_transpose_kn(const float* W, int K, int N, bf16_t* WT, int row_off, LAS float* scr, int kb, int nb, int lane) {
;     ...
;     for (int i = 0; i < 32; ++i) wv[i] = W[(size_t)(k0 + 2 * i + (lane >> 5)) * N + n0 + (lane & 31)];
; #pragma unroll
;     for (int i = 0; i < 32; ++i) scr[(2 * i + (lane >> 5)) * 33 + (lane & 31)] = wv[i];
;     asm volatile("s_waitcnt lgkmcnt(0)" ::: "memory");
;     const int c = lane & 7;
; #pragma unroll
;     for (int j = 0; j < 4; ++j) { const int n = (lane >> 3) + 8 * j; const LAS float* s = scr + (8 * c) * 33 + n;
;         u32x4 o; o.x = pk2(s[0 * 33], s[1 * 33]); o.y = pk2(s[2 * 33], s[3 * 33]); o.z = pk2(s[4 * 33], s[5 * 33]); o.w = pk2(s[6 * 33], s[7 * 33]);
;         *(u32x4*)(WT + (size_t)(row_off + n0 + n) * K + k0 + 8 * c) = o; }
;     asm volatile("s_waitcnt lgkmcnt(0)" ::: "memory");
.Ldry_cvD_c3:
	global_load_dword v40, v[42:43], off
	global_load_dword v41, v[44:45], off
	s_nop 0
	global_load_dword v42, v[46:47], off
	global_load_dword v43, v[48:49], off
	global_load_dword v44, v[50:51], off
	global_load_dword v45, v[52:53], off
	s_nop 0
	global_load_dword v38, v[38:39], off
	s_waitcnt vmcnt(0)
	ds_write2_b32 v19, v17, v35 offset1:66
	ds_write2_b32 v19, v37, v56 offset0:132 offset1:198
	ds_write2_b32 v27, v57, v58 offset0:8 offset1:74
	ds_write2_b32 v27, v59, v60 offset0:140 offset1:206
	ds_write2_b32 v28, v61, v62 offset0:16 offset1:82
	ds_write2_b32 v28, v63, v64 offset0:148 offset1:214
	ds_write2_b32 v29, v65, v66 offset0:24 offset1:90
	ds_write2_b32 v29, v67, v68 offset0:156 offset1:222
	ds_write2_b32 v30, v69, v70 offset0:32 offset1:98
	ds_write2_b32 v30, v71, v72 offset0:164 offset1:230
	ds_write2_b32 v31, v73, v74 offset0:40 offset1:106
	ds_write2_b32 v31, v75, v54 offset0:172 offset1:238
	ds_write2_b32 v32, v0, v40 offset0:48 offset1:114
	ds_write2_b32 v32, v41, v42 offset0:180 offset1:246
	ds_write2_b32 v33, v43, v44 offset0:56 offset1:122
	ds_write2_b32 v33, v45, v38 offset0:188 offset1:254
	s_waitcnt lgkmcnt(0)
	ds_read2_b32 v[40:41], v21 offset1:8
	ds_read2_b32 v[44:45], v21 offset0:33 offset1:41
	ds_read2_b32 v[46:47], v21 offset0:66 offset1:74
	ds_read2_b32 v[48:49], v21 offset0:99 offset1:107
	ds_read2_b32 v[50:51], v21 offset0:132 offset1:140
	s_waitcnt lgkmcnt(4)
	v_bfe_u32 v0, v40, 16, 1
	v_add3_u32 v0, v40, v0, s19
	s_waitcnt lgkmcnt(3)
	s_cbranch_execz .Ldry_cvD_real
.Ldry_cvD_c4:
	v_bfe_u32 v17, v44, 16, 1
	v_ashrrev_i32_e32 v37, 31, v36
	v_lshrrev_b32_e32 v0, 16, v0
	v_add3_u32 v17, v44, v17, s19
	ds_read2_b32 v[52:53], v21 offset0:165 offset1:173
	v_lshl_add_u64 v[42:43], v[36:37], 1, v[14:15]
	v_and_or_b32 v36, v17, s20, v0
	s_waitcnt lgkmcnt(3)
	v_bfe_u32 v0, v46, 16, 1
	v_add3_u32 v0, v46, v0, s19
	s_waitcnt lgkmcnt(2)
	v_bfe_u32 v17, v48, 16, 1
	ds_read2_b32 v[54:55], v21 offset0:198 offset1:206
	v_lshrrev_b32_e32 v0, 16, v0
	v_add3_u32 v17, v48, v17, s19
	ds_read2_b32 v[56:57], v21 offset0:231 offset1:239
	v_and_or_b32 v37, v17, s20, v0
	s_waitcnt lgkmcnt(3)
	v_bfe_u32 v0, v50, 16, 1
	v_add3_u32 v0, v50, v0, s19
	s_waitcnt lgkmcnt(2)
	v_bfe_u32 v17, v52, 16, 1
	v_lshrrev_b32_e32 v0, 16, v0
	v_add3_u32 v17, v52, v17, s19
	v_and_or_b32 v38, v17, s20, v0
	s_waitcnt lgkmcnt(1)
	v_bfe_u32 v0, v54, 16, 1
	v_add3_u32 v0, v54, v0, s19
	s_waitcnt lgkmcnt(0)
	v_bfe_u32 v17, v56, 16, 1
	v_lshrrev_b32_e32 v0, 16, v0
	v_add3_u32 v17, v56, v17, s19
	v_or_b32_e32 v58, v16, v20
	v_and_or_b32 v39, v17, s20, v0
	v_ashrrev_i32_e32 v59, 31, v58
	v_bfe_u32 v0, v41, 16, 1
	s_cbranch_execz .Ldry_cvD_real
.Ldry_cvD_c5:
	v_lshlrev_b64 v[58:59], 11, v[58:59]
	v_add3_u32 v0, v41, v0, s19
	v_bfe_u32 v17, v45, 16, 1
	v_lshl_add_u64 v[58:59], v[42:43], 0, v[58:59]
	v_lshrrev_b32_e32 v0, 16, v0
	v_add3_u32 v17, v45, v17, s19
	global_store_dwordx4 v[58:59], v[36:39], off
	v_or_b32_e32 v40, v16, v22
	v_ashrrev_i32_e32 v41, 31, v40
	v_and_or_b32 v36, v17, s20, v0
	v_bfe_u32 v0, v47, 16, 1
	v_add3_u32 v0, v47, v0, s19
	v_bfe_u32 v17, v49, 16, 1
	v_lshrrev_b32_e32 v0, 16, v0
	v_add3_u32 v17, v49, v17, s19
	v_and_or_b32 v37, v17, s20, v0
	v_bfe_u32 v0, v51, 16, 1
	v_add3_u32 v0, v51, v0, s19
	v_bfe_u32 v17, v53, 16, 1
	v_lshrrev_b32_e32 v0, 16, v0
	v_add3_u32 v17, v53, v17, s19
	v_and_or_b32 v38, v17, s20, v0
	v_bfe_u32 v0, v55, 16, 1
	v_add3_u32 v0, v55, v0, s19
	v_bfe_u32 v17, v57, 16, 1
	v_lshrrev_b32_e32 v0, 16, v0
	v_add3_u32 v17, v57, v17, s19
	v_lshlrev_b64 v[40:41], 11, v[40:41]
	v_and_or_b32 v39, v17, s20, v0
	ds_read2_b32 v[44:45], v21 offset0:16 offset1:24
	v_lshl_add_u64 v[40:41], v[42:43], 0, v[40:41]
	global_store_dwordx4 v[40:41], v[36:39], off
	ds_read2_b32 v[40:41], v21 offset0:49 offset1:57
	ds_read2_b32 v[46:47], v21 offset0:82 offset1:90
	ds_read2_b32 v[48:49], v21 offset0:115 offset1:123
	s_cbranch_execz .Ldry_cvD_real
.Ldry_cvD_c6:
	s_waitcnt lgkmcnt(3)
	v_bfe_u32 v0, v44, 16, 1
	v_add3_u32 v0, v44, v0, s19
	s_waitcnt lgkmcnt(2)
	v_bfe_u32 v17, v40, 16, 1
	ds_read2_b32 v[50:51], v21 offset0:148 offset1:156
	v_lshrrev_b32_e32 v0, 16, v0
	v_add3_u32 v17, v40, v17, s19
	ds_read2_b32 v[52:53], v21 offset0:181 offset1:189
	v_and_or_b32 v36, v17, s20, v0
	s_waitcnt lgkmcnt(3)
	v_bfe_u32 v0, v46, 16, 1
	v_add3_u32 v0, v46, v0, s19
	s_waitcnt lgkmcnt(2)
	v_bfe_u32 v17, v48, 16, 1
	ds_read2_b32 v[54:55], v21 offset0:214 offset1:222
	v_lshrrev_b32_e32 v0, 16, v0
	v_add3_u32 v17, v48, v17, s19
	ds_read2_b32 v[56:57], v21 offset0:247 offset1:255
	v_and_or_b32 v37, v17, s20, v0
	s_waitcnt lgkmcnt(3)
	v_bfe_u32 v0, v50, 16, 1
	v_add3_u32 v0, v50, v0, s19
	s_waitcnt lgkmcnt(2)
	v_bfe_u32 v17, v52, 16, 1
	v_lshrrev_b32_e32 v0, 16, v0
	v_add3_u32 v17, v52, v17, s19
	v_and_or_b32 v38, v17, s20, v0
	s_waitcnt lgkmcnt(1)
	v_bfe_u32 v0, v54, 16, 1
	v_add3_u32 v0, v54, v0, s19
	s_waitcnt lgkmcnt(0)
	v_bfe_u32 v17, v56, 16, 1
	v_lshrrev_b32_e32 v0, 16, v0
	v_add3_u32 v17, v56, v17, s19
	v_or_b32_e32 v58, v16, v23
	s_cbranch_execz .Ldry_cvD_real
.Ldry_cvD_c7:
	v_and_or_b32 v39, v17, s20, v0
	v_ashrrev_i32_e32 v59, 31, v58
	v_bfe_u32 v0, v45, 16, 1
	v_lshlrev_b64 v[58:59], 11, v[58:59]
	v_add3_u32 v0, v45, v0, s19
	v_bfe_u32 v17, v41, 16, 1
	v_lshl_add_u64 v[58:59], v[42:43], 0, v[58:59]
	v_lshrrev_b32_e32 v0, 16, v0
	v_add3_u32 v17, v41, v17, s19
	global_store_dwordx4 v[58:59], v[36:39], off
	v_or_b32_e32 v16, v16, v24
	s_nop 0
	v_and_or_b32 v36, v17, s20, v0
	v_bfe_u32 v0, v47, 16, 1
	v_add3_u32 v0, v47, v0, s19
	v_bfe_u32 v17, v49, 16, 1
	v_lshrrev_b32_e32 v0, 16, v0
	v_add3_u32 v17, v49, v17, s19
	v_and_or_b32 v37, v17, s20, v0
	v_bfe_u32 v0, v51, 16, 1
	v_add3_u32 v0, v51, v0, s19
	v_bfe_u32 v17, v53, 16, 1
	v_lshrrev_b32_e32 v0, 16, v0
	v_add3_u32 v17, v53, v17, s19
	v_and_or_b32 v38, v17, s20, v0
	v_bfe_u32 v0, v55, 16, 1
	v_add3_u32 v0, v55, v0, s19
	v_bfe_u32 v17, v57, 16, 1
	v_lshrrev_b32_e32 v0, 16, v0
	v_add3_u32 v17, v57, v17, s19
	v_and_or_b32 v39, v17, s20, v0
	v_ashrrev_i32_e32 v17, 31, v16
	v_lshlrev_b64 v[16:17], 11, v[16:17]
	v_lshl_add_u64 v[16:17], v[42:43], 0, v[16:17]
	global_store_dwordx4 v[16:17], v[36:39], off
	s_waitcnt lgkmcnt(0)
	s_cbranch_execz .Ldry_cvD_real
	s_branch .LBB0_402
